# DSA attention chunk rewritten: key fragments and bias lookups issued up front, two score tiles interleaved, validity selects skipped for fully valid chunks, row-max DPP chains interleaved, packed f32
# speedup vs baseline: 1.0109x; 1.0043x over previous
.LBB0_2489:
	s_waitcnt lgkmcnt(0)
	s_andn2_b64 vcc, exec, s[28:29]
	s_cbranch_vccnz .LBB0_1626
	s_add_i32 s6, s54, s16
	s_ashr_i32 s7, s6, 31
	s_lshl_b64 s[10:11], s[6:7], 12
	v_lshl_add_u64 v[2:3], v[170:171], 0, s[10:11]
	global_load_dwordx4 v[4:7], v[2:3], off
	global_load_dwordx4 v[8:11], v[2:3], off offset:64
	global_load_dwordx4 v[12:15], v[2:3], off offset:128
	global_load_dwordx4 v[16:19], v[2:3], off offset:192
	s_lshl_b32 s16, s16, 8
	v_readfirstlane_b32 s96, v174
	v_readfirstlane_b32 s97, v175
	v_and_b32_e32 v152, 15, v192
	v_lshlrev_b32_e32 v152, 4, v152
	s_nop 1
	s_add_u32 s96, s96, s16
	s_addc_u32 s97, s97, 0
	s_mov_b32 s94, 0x3fb8aa3b
	s_mov_b32 s95, 0x3fb8aa3b
	s_mov_b32 s98, 0x22800
	s_movk_i32 s99, 0x7f
	v_add_u32_e32 v153, 0x20000, v214
	ds_read_b32 v20, v213
	ds_read_b32 v24, v213 offset:16
	ds_read_b32 v28, v213 offset:32
	ds_read_b32 v64, v213 offset:48
	ds_read_b32 v72, v213 offset:64
	ds_read_b32 v80, v213 offset:80
	ds_read_b32 v88, v213 offset:96
	ds_read_b32 v96, v213 offset:112
	ds_read_b32 v68, v213 offset:128
	ds_read_b32 v76, v213 offset:144
	ds_read_b32 v84, v213 offset:160
	ds_read_b32 v92, v213 offset:176
	ds_read_b32 v100, v213 offset:192
	ds_read_b32 v104, v213 offset:208
	ds_read_b32 v108, v213 offset:224
	ds_read_b32 v112, v213 offset:240
	s_waitcnt lgkmcnt(0)
	v_lshl_or_b32 v20, v20, 8, v152
	global_load_dwordx4 v[20:23], v20, s[96:97]
	v_lshl_or_b32 v24, v24, 8, v152
	global_load_dwordx4 v[24:27], v24, s[96:97]
	v_lshl_or_b32 v28, v28, 8, v152
	global_load_dwordx4 v[28:31], v28, s[96:97]
	v_lshl_or_b32 v64, v64, 8, v152
	global_load_dwordx4 v[64:67], v64, s[96:97]
	v_lshl_or_b32 v72, v72, 8, v152
	global_load_dwordx4 v[72:75], v72, s[96:97]
	v_lshl_or_b32 v80, v80, 8, v152
	global_load_dwordx4 v[80:83], v80, s[96:97]
	v_lshl_or_b32 v88, v88, 8, v152
	global_load_dwordx4 v[88:91], v88, s[96:97]
	v_lshl_or_b32 v96, v96, 8, v152
	global_load_dwordx4 v[96:99], v96, s[96:97]
	v_lshl_or_b32 v68, v68, 8, v152
	global_load_dwordx4 v[68:71], v68, s[96:97]
	v_lshl_or_b32 v76, v76, 8, v152
	global_load_dwordx4 v[76:79], v76, s[96:97]
	v_lshl_or_b32 v84, v84, 8, v152
	global_load_dwordx4 v[84:87], v84, s[96:97]
	v_lshl_or_b32 v92, v92, 8, v152
	global_load_dwordx4 v[92:95], v92, s[96:97]
	v_lshl_or_b32 v100, v100, 8, v152
	global_load_dwordx4 v[100:103], v100, s[96:97]
	v_lshl_or_b32 v104, v104, 8, v152
	global_load_dwordx4 v[104:107], v104, s[96:97]
	v_lshl_or_b32 v108, v108, 8, v152
	global_load_dwordx4 v[108:111], v108, s[96:97]
	v_lshl_or_b32 v112, v112, 8, v152
	global_load_dwordx4 v[112:115], v112, s[96:97]
	s_add_i32 s6, s40, 31
	s_ashr_i32 s16, s6, 5
	s_cmp_gt_i32 s16, 0
	s_cbranch_scc0 .LBB0_1624
	v_mov_b32_e32 v2, v1
	v_mov_b32_e32 v3, v1
	v_mov_b32_e32 v0, v1
	v_mov_b32_e32 v154, 0
	v_mov_b64_e32 v[34:35], v[2:3]
	v_mov_b64_e32 v[38:39], v[2:3]
	v_mov_b64_e32 v[42:43], v[2:3]
	v_mov_b64_e32 v[46:47], v[2:3]
	v_mov_b64_e32 v[50:51], v[2:3]
	v_mov_b64_e32 v[54:55], v[2:3]
	v_mov_b64_e32 v[58:59], v[2:3]
	v_mov_b64_e32 v[62:63], v[2:3]
	s_mov_b32 s41, 0
	v_mov_b32_e32 v230, 0xff800000
	s_mov_b32 s55, 3
	s_mov_b32 s57, s42
	v_mov_b64_e32 v[32:33], v[0:1]
	v_mov_b64_e32 v[36:37], v[0:1]
	v_mov_b64_e32 v[40:41], v[0:1]
	v_mov_b64_e32 v[44:45], v[0:1]
	v_mov_b64_e32 v[48:49], v[0:1]
	v_mov_b64_e32 v[52:53], v[0:1]
	v_mov_b64_e32 v[56:57], v[0:1]
	v_mov_b64_e32 v[60:61], v[0:1]
	v_mov_b32_e32 v231, 0xff800000
	v_mov_b32_e32 v232, 0xff800000
	v_mov_b32_e32 v233, 0xff800000
	v_mov_b32_e32 v155, v154
	v_mov_b32_e32 v156, v154
	v_mov_b32_e32 v157, v154
	s_branch .LBB0_2526
.LBB0_2524:
.LBB0_2525:
	s_addk_i32 s57, 0x100
	s_add_i32 s41, s41, 64
	s_add_i32 s55, s55, 2
	s_cmp_ge_i32 s58, s16
	s_cbranch_scc1 .LBB0_1625

.LBB0_2544:
	s_waitcnt lgkmcnt(0)
	v_add_u32_e32 v228, s57, v153
	ds_read_b32 v158, v228
	ds_read_b32 v159, v228 offset:64
	ds_read_b128 v[116:119], v219
	ds_read_b128 v[120:123], v219 offset:64
	ds_read_b128 v[124:127], v219 offset:128
	ds_read_b128 v[128:131], v219 offset:192
	ds_read_b128 v[132:135], v219 offset:4352
	ds_read_b128 v[136:139], v219 offset:4416
	ds_read_b128 v[140:143], v219 offset:4480
	ds_read_b128 v[144:147], v219 offset:4544
	s_sub_i32 s6, s40, s41
	s_add_i32 s7, s6, -16
	s_waitcnt lgkmcnt(8)
	v_sub_u32_e32 v158, s54, v158
	v_sub_u32_e32 v159, s54, v159
	v_med3_i32 v158, v158, 0, s99
	v_med3_i32 v159, v159, 0, s99
	v_lshl_add_u32 v158, v158, 2, s98
	v_lshl_add_u32 v159, v159, 2, s98
	ds_read_b32 v158, v158
	ds_read_b32 v159, v159
	s_waitcnt lgkmcnt(9)
	v_mfma_f32_16x16x32_bf16 v[116:119], v[4:7], v[116:119], 0
	s_waitcnt lgkmcnt(5)
	v_mfma_f32_16x16x32_bf16 v[132:135], v[4:7], v[132:135], 0
	v_mfma_f32_16x16x32_bf16 v[116:119], v[8:11], v[120:123], v[116:119]
	s_waitcnt lgkmcnt(4)
	v_mfma_f32_16x16x32_bf16 v[132:135], v[8:11], v[136:139], v[132:135]
	v_mfma_f32_16x16x32_bf16 v[116:119], v[12:15], v[124:127], v[116:119]
	s_waitcnt lgkmcnt(3)
	v_mfma_f32_16x16x32_bf16 v[132:135], v[12:15], v[140:143], v[132:135]
	v_mfma_f32_16x16x32_bf16 v[116:119], v[16:19], v[128:131], v[116:119]
	s_waitcnt lgkmcnt(2)
	v_mfma_f32_16x16x32_bf16 v[132:135], v[16:19], v[144:147], v[132:135]
	s_nop 3
	s_waitcnt lgkmcnt(0)
	v_lshl_add_u32 v158, v158, 6, v191
	v_lshl_add_u32 v159, v159, 6, v191
	ds_read_b128 v[180:183], v158
	ds_read_b128 v[148:151], v159
	s_cmp_ge_i32 s6, 32
	s_waitcnt lgkmcnt(0)
	v_add_f32_e32 v120, v116, v180
	v_add_f32_e32 v121, v132, v148
	v_add_f32_e32 v122, v117, v181
	v_add_f32_e32 v123, v133, v149
	v_add_f32_e32 v124, v118, v182
	v_add_f32_e32 v125, v134, v150
	v_add_f32_e32 v126, v119, v183
	v_add_f32_e32 v127, v135, v151
	s_cbranch_scc1 .Lat_av_A
	v_cmp_gt_i32_e32 vcc, s6, v187
	v_cmp_gt_i32_e64 s[8:9], s7, v187
	s_nop 1
	v_cndmask_b32_e32 v120, v220, v120, vcc
	v_cndmask_b32_e32 v122, v220, v122, vcc
	v_cndmask_b32_e32 v124, v220, v124, vcc
	v_cndmask_b32_e32 v126, v220, v126, vcc
	v_cndmask_b32_e64 v121, v220, v121, s[8:9]
	v_cndmask_b32_e64 v123, v220, v123, s[8:9]
	v_cndmask_b32_e64 v125, v220, v125, s[8:9]
	v_cndmask_b32_e64 v127, v220, v127, s[8:9]
.Lat_av_A:
	v_max_f32_e32 v2, v120, v121
	v_max_f32_e32 v3, v122, v123
	v_max_f32_e32 v158, v124, v125
	v_max_f32_e32 v159, v126, v127
	v_max_f32_dpp v2, v2, v2 quad_perm:[1,0,3,2] row_mask:0xf bank_mask:0xf bound_ctrl:1
	v_max_f32_dpp v3, v3, v3 quad_perm:[1,0,3,2] row_mask:0xf bank_mask:0xf bound_ctrl:1
	v_max_f32_dpp v158, v158, v158 quad_perm:[1,0,3,2] row_mask:0xf bank_mask:0xf bound_ctrl:1
	v_max_f32_dpp v159, v159, v159 quad_perm:[1,0,3,2] row_mask:0xf bank_mask:0xf bound_ctrl:1
	v_max_f32_dpp v2, v2, v2 quad_perm:[2,3,0,1] row_mask:0xf bank_mask:0xf bound_ctrl:1
	v_max_f32_dpp v3, v3, v3 quad_perm:[2,3,0,1] row_mask:0xf bank_mask:0xf bound_ctrl:1
	v_max_f32_dpp v158, v158, v158 quad_perm:[2,3,0,1] row_mask:0xf bank_mask:0xf bound_ctrl:1
	v_max_f32_dpp v159, v159, v159 quad_perm:[2,3,0,1] row_mask:0xf bank_mask:0xf bound_ctrl:1
	v_max_f32_dpp v2, v2, v2 row_half_mirror row_mask:0xf bank_mask:0xf bound_ctrl:1
	v_max_f32_dpp v3, v3, v3 row_half_mirror row_mask:0xf bank_mask:0xf bound_ctrl:1
	v_max_f32_dpp v158, v158, v158 row_half_mirror row_mask:0xf bank_mask:0xf bound_ctrl:1
	v_max_f32_dpp v159, v159, v159 row_half_mirror row_mask:0xf bank_mask:0xf bound_ctrl:1
	v_mov_b32_dpp v128, v2 row_mirror row_mask:0xf bank_mask:0xf bound_ctrl:1
	v_mov_b32_dpp v129, v3 row_mirror row_mask:0xf bank_mask:0xf bound_ctrl:1
	v_mov_b32_dpp v130, v158 row_mirror row_mask:0xf bank_mask:0xf bound_ctrl:1
	v_mov_b32_dpp v131, v159 row_mirror row_mask:0xf bank_mask:0xf bound_ctrl:1
	v_max3_f32 v239, v233, v2, v128
	v_max3_f32 v238, v232, v3, v129
	v_max3_f32 v151, v231, v158, v130
	v_max3_f32 v150, v230, v159, v131
	v_pk_add_f32 v[160:161], v[232:233], v[238:239] neg_lo:[0,1] neg_hi:[0,1]
	v_pk_add_f32 v[184:185], v[230:231], v[150:151] neg_lo:[0,1] neg_hi:[0,1]
	v_pk_add_f32 v[120:121], v[120:121], v[238:239] op_sel:[0,1] op_sel_hi:[1,1] neg_lo:[0,1] neg_hi:[0,1]
	v_pk_add_f32 v[122:123], v[122:123], v[238:239] op_sel:[0,0] op_sel_hi:[1,0] neg_lo:[0,1] neg_hi:[0,1]
	v_pk_add_f32 v[124:125], v[124:125], v[150:151] op_sel:[0,1] op_sel_hi:[1,1] neg_lo:[0,1] neg_hi:[0,1]
	v_pk_add_f32 v[126:127], v[126:127], v[150:151] op_sel:[0,0] op_sel_hi:[1,0] neg_lo:[0,1] neg_hi:[0,1]
	v_mov_b64_e32 v[232:233], v[238:239]
	v_mov_b64_e32 v[230:231], v[150:151]
	v_pk_mul_f32 v[120:121], v[120:121], s[94:95]
	v_pk_mul_f32 v[122:123], v[122:123], s[94:95]
	v_pk_mul_f32 v[124:125], v[124:125], s[94:95]
	v_pk_mul_f32 v[126:127], v[126:127], s[94:95]
	v_pk_mul_f32 v[160:161], v[160:161], s[94:95]
	v_pk_mul_f32 v[184:185], v[184:185], s[94:95]
	v_exp_f32_e32 v3, v120
	v_exp_f32_e32 v159, v121
	v_exp_f32_e32 v2, v122
	v_exp_f32_e32 v158, v123
	v_exp_f32_e32 v181, v124
	v_exp_f32_e32 v183, v125
	v_exp_f32_e32 v180, v126
	v_exp_f32_e32 v182, v127
	v_exp_f32_e32 v161, v161
	v_exp_f32_e32 v160, v160
	v_exp_f32_e32 v185, v185
	v_exp_f32_e32 v184, v184
	v_cvt_pk_bf16_f32 v128, v3, v159
	v_cvt_pk_bf16_f32 v129, v2, v158
	v_cvt_pk_bf16_f32 v130, v181, v183
	v_cvt_pk_bf16_f32 v131, v180, v182
	ds_write_b16 v221, v128 offset:8704
	ds_write_b16_d16_hi v221, v128 offset:8736
	ds_write_b16 v221, v129 offset:8784
	ds_write_b16_d16_hi v221, v129 offset:8816
	ds_write_b16 v221, v130 offset:8864
	ds_write_b16_d16_hi v221, v130 offset:8896
	ds_write_b16 v221, v131 offset:8944
	ds_write_b16_d16_hi v221, v131 offset:8976
	v_min3_f32 v0, v161, v160, v185
	v_min_f32_e32 v0, v0, v184
	s_waitcnt lgkmcnt(0)
	ds_read_b128 v[116:119], v222 offset:8704
	ds_read_b64_tr_b16 v[148:149], v193 offset:0
	ds_read_b64_tr_b16 v[150:151], v193 offset:1088
	ds_read_b64_tr_b16 v[144:145], v193 offset:32
	ds_read_b64_tr_b16 v[146:147], v193 offset:1120
	ds_read_b64_tr_b16 v[140:141], v193 offset:64
	ds_read_b64_tr_b16 v[142:143], v193 offset:1152
	ds_read_b64_tr_b16 v[136:137], v193 offset:96
	ds_read_b64_tr_b16 v[138:139], v193 offset:1184
	ds_read_b64_tr_b16 v[132:133], v193 offset:128
	ds_read_b64_tr_b16 v[134:135], v193 offset:1216
	ds_read_b64_tr_b16 v[128:129], v193 offset:160
	ds_read_b64_tr_b16 v[130:131], v193 offset:1248
	ds_read_b64_tr_b16 v[124:125], v193 offset:192
	ds_read_b64_tr_b16 v[126:127], v193 offset:1280
	ds_read_b64_tr_b16 v[120:121], v193 offset:224
	ds_read_b64_tr_b16 v[122:123], v193 offset:1312
	v_cmp_neq_f32_e32 vcc, 1.0, v0
	s_cbranch_vccz .Lat_nr_A
	v_pk_mul_f32 v[60:61], v[60:61], v[160:161] op_sel:[0,1] op_sel_hi:[1,0]
	v_pk_mul_f32 v[62:63], v[62:63], v[184:185] op_sel:[0,1] op_sel_hi:[1,0]
	v_pk_mul_f32 v[56:57], v[56:57], v[160:161] op_sel:[0,1] op_sel_hi:[1,0]
	v_pk_mul_f32 v[58:59], v[58:59], v[184:185] op_sel:[0,1] op_sel_hi:[1,0]
	v_pk_mul_f32 v[52:53], v[52:53], v[160:161] op_sel:[0,1] op_sel_hi:[1,0]
	v_pk_mul_f32 v[54:55], v[54:55], v[184:185] op_sel:[0,1] op_sel_hi:[1,0]
	v_pk_mul_f32 v[48:49], v[48:49], v[160:161] op_sel:[0,1] op_sel_hi:[1,0]
	v_pk_mul_f32 v[50:51], v[50:51], v[184:185] op_sel:[0,1] op_sel_hi:[1,0]
	v_pk_mul_f32 v[44:45], v[44:45], v[160:161] op_sel:[0,1] op_sel_hi:[1,0]
	v_pk_mul_f32 v[46:47], v[46:47], v[184:185] op_sel:[0,1] op_sel_hi:[1,0]
	v_pk_mul_f32 v[40:41], v[40:41], v[160:161] op_sel:[0,1] op_sel_hi:[1,0]
	v_pk_mul_f32 v[42:43], v[42:43], v[184:185] op_sel:[0,1] op_sel_hi:[1,0]
	v_pk_mul_f32 v[36:37], v[36:37], v[160:161] op_sel:[0,1] op_sel_hi:[1,0]
	v_pk_mul_f32 v[38:39], v[38:39], v[184:185] op_sel:[0,1] op_sel_hi:[1,0]
	v_pk_mul_f32 v[32:33], v[32:33], v[160:161] op_sel:[0,1] op_sel_hi:[1,0]
	v_pk_mul_f32 v[34:35], v[34:35], v[184:185] op_sel:[0,1] op_sel_hi:[1,0]
.Lat_nr_A:
	s_waitcnt lgkmcnt(0)
	v_mfma_f32_16x16x32_bf16 v[60:63], v[116:119], v[148:151], v[60:63]
	v_pk_fma_f32 v[2:3], v[156:157], v[160:161], v[2:3]
	v_pk_add_f32 v[156:157], v[158:159], v[2:3]
	v_mfma_f32_16x16x32_bf16 v[56:59], v[116:119], v[144:147], v[56:59]
	v_pk_fma_f32 v[2:3], v[154:155], v[184:185], v[180:181]
	v_pk_add_f32 v[154:155], v[182:183], v[2:3]
	s_add_i32 s6, s55, -2
	s_cmp_ge_i32 s6, s16
	v_mfma_f32_16x16x32_bf16 v[52:55], v[116:119], v[140:143], v[52:55]
	v_mfma_f32_16x16x32_bf16 v[48:51], v[116:119], v[136:139], v[48:51]
	v_mfma_f32_16x16x32_bf16 v[44:47], v[116:119], v[132:135], v[44:47]
	v_mfma_f32_16x16x32_bf16 v[40:43], v[116:119], v[128:131], v[40:43]
	v_mfma_f32_16x16x32_bf16 v[36:39], v[116:119], v[124:127], v[36:39]
	v_mfma_f32_16x16x32_bf16 v[32:35], v[116:119], v[120:123], v[32:35]
	s_cbranch_scc1 .LBB0_2524
	s_cmp_ge_i32 s55, s16
	ds_write_b128 v218, v[68:71]
	ds_write_b128 v218, v[76:79] offset:1088
	ds_write_b128 v218, v[84:87] offset:2176
	ds_write_b128 v218, v[92:95] offset:3264
	ds_write_b128 v218, v[100:103] offset:4352
	ds_write_b128 v218, v[104:107] offset:5440
	ds_write_b128 v218, v[108:111] offset:6528
	ds_write_b128 v218, v[112:115] offset:7616
	s_cbranch_scc1 .LBB0_2573
	v_add_u32_e32 v114, s57, v212
	v_add_u32_e32 v114, 0x20180, v114
	ds_read_b32 v68, v114
	ds_read_b32 v76, v114 offset:16
	ds_read_b32 v84, v114 offset:32
	ds_read_b32 v92, v114 offset:48
	ds_read_b32 v100, v114 offset:64
	ds_read_b32 v104, v114 offset:80
	ds_read_b32 v108, v114 offset:96
	ds_read_b32 v112, v114 offset:112
	s_waitcnt lgkmcnt(0)
	v_lshl_or_b32 v68, v68, 8, v152
	global_load_dwordx4 v[68:71], v68, s[96:97]
	v_lshl_or_b32 v76, v76, 8, v152
	global_load_dwordx4 v[76:79], v76, s[96:97]
	v_lshl_or_b32 v84, v84, 8, v152
	global_load_dwordx4 v[84:87], v84, s[96:97]
	v_lshl_or_b32 v92, v92, 8, v152
	global_load_dwordx4 v[92:95], v92, s[96:97]
	v_lshl_or_b32 v100, v100, 8, v152
	global_load_dwordx4 v[100:103], v100, s[96:97]
	v_lshl_or_b32 v104, v104, 8, v152
	global_load_dwordx4 v[104:107], v104, s[96:97]
	v_lshl_or_b32 v108, v108, 8, v152
	global_load_dwordx4 v[108:111], v108, s[96:97]
	v_lshl_or_b32 v112, v112, 8, v152
	global_load_dwordx4 v[112:115], v112, s[96:97]
.LBB0_2573:
	s_waitcnt lgkmcnt(0)
	ds_read_b32 v158, v228 offset:128
	ds_read_b32 v159, v228 offset:192
	ds_read_b128 v[116:119], v219
	ds_read_b128 v[120:123], v219 offset:64
	ds_read_b128 v[124:127], v219 offset:128
	ds_read_b128 v[128:131], v219 offset:192
	ds_read_b128 v[132:135], v219 offset:4352
	ds_read_b128 v[136:139], v219 offset:4416
	ds_read_b128 v[140:143], v219 offset:4480
	ds_read_b128 v[144:147], v219 offset:4544
	s_sub_i32 s6, s40, s41
	s_sub_i32 s6, s6, 32
	s_add_i32 s7, s6, -16
	s_waitcnt lgkmcnt(8)
	v_sub_u32_e32 v158, s54, v158
	v_sub_u32_e32 v159, s54, v159
	v_med3_i32 v158, v158, 0, s99
	v_med3_i32 v159, v159, 0, s99
	v_lshl_add_u32 v158, v158, 2, s98
	v_lshl_add_u32 v159, v159, 2, s98
	ds_read_b32 v158, v158
	ds_read_b32 v159, v159
	s_waitcnt lgkmcnt(9)
	v_mfma_f32_16x16x32_bf16 v[116:119], v[4:7], v[116:119], 0
	s_waitcnt lgkmcnt(5)
	v_mfma_f32_16x16x32_bf16 v[132:135], v[4:7], v[132:135], 0
	v_mfma_f32_16x16x32_bf16 v[116:119], v[8:11], v[120:123], v[116:119]
	s_waitcnt lgkmcnt(4)
	v_mfma_f32_16x16x32_bf16 v[132:135], v[8:11], v[136:139], v[132:135]
	v_mfma_f32_16x16x32_bf16 v[116:119], v[12:15], v[124:127], v[116:119]
	s_waitcnt lgkmcnt(3)
	v_mfma_f32_16x16x32_bf16 v[132:135], v[12:15], v[140:143], v[132:135]
	v_mfma_f32_16x16x32_bf16 v[116:119], v[16:19], v[128:131], v[116:119]
	s_waitcnt lgkmcnt(2)
	v_mfma_f32_16x16x32_bf16 v[132:135], v[16:19], v[144:147], v[132:135]
	s_nop 3
	s_waitcnt lgkmcnt(0)
	v_lshl_add_u32 v158, v158, 6, v191
	v_lshl_add_u32 v159, v159, 6, v191
	ds_read_b128 v[180:183], v158
	ds_read_b128 v[148:151], v159
	s_cmp_ge_i32 s6, 32
	s_waitcnt lgkmcnt(0)
	v_add_f32_e32 v120, v116, v180
	v_add_f32_e32 v121, v132, v148
	v_add_f32_e32 v122, v117, v181
	v_add_f32_e32 v123, v133, v149
	v_add_f32_e32 v124, v118, v182
	v_add_f32_e32 v125, v134, v150
	v_add_f32_e32 v126, v119, v183
	v_add_f32_e32 v127, v135, v151
	s_cbranch_scc1 .Lat_av_B
	v_cmp_gt_i32_e32 vcc, s6, v187
	v_cmp_gt_i32_e64 s[8:9], s7, v187
	s_nop 1
	v_cndmask_b32_e32 v120, v220, v120, vcc
	v_cndmask_b32_e32 v122, v220, v122, vcc
	v_cndmask_b32_e32 v124, v220, v124, vcc
	v_cndmask_b32_e32 v126, v220, v126, vcc
	v_cndmask_b32_e64 v121, v220, v121, s[8:9]
	v_cndmask_b32_e64 v123, v220, v123, s[8:9]
	v_cndmask_b32_e64 v125, v220, v125, s[8:9]
	v_cndmask_b32_e64 v127, v220, v127, s[8:9]

.Lat_nr_B:
	s_waitcnt lgkmcnt(0)
	v_mfma_f32_16x16x32_bf16 v[60:63], v[116:119], v[148:151], v[60:63]
	v_pk_fma_f32 v[2:3], v[156:157], v[160:161], v[2:3]
	v_pk_add_f32 v[156:157], v[158:159], v[2:3]
	v_mfma_f32_16x16x32_bf16 v[56:59], v[116:119], v[144:147], v[56:59]
	v_pk_fma_f32 v[2:3], v[154:155], v[184:185], v[180:181]
	v_pk_add_f32 v[154:155], v[182:183], v[2:3]
	v_mfma_f32_16x16x32_bf16 v[52:55], v[116:119], v[140:143], v[52:55]
	v_mfma_f32_16x16x32_bf16 v[48:51], v[116:119], v[136:139], v[48:51]
	v_mfma_f32_16x16x32_bf16 v[44:47], v[116:119], v[132:135], v[44:47]
	v_mfma_f32_16x16x32_bf16 v[40:43], v[116:119], v[128:131], v[40:43]
	v_mfma_f32_16x16x32_bf16 v[36:39], v[116:119], v[124:127], v[36:39]
	v_mfma_f32_16x16x32_bf16 v[32:35], v[116:119], v[120:123], v[32:35]
	s_branch .LBB0_2525
